# wide conversion routine also for RG_IN (96 workgroups idle in the last round of the layer-0 w_in GEMM)
# speedup vs baseline: 1.0032x; 1.0032x over previous
; template <class CM, class RM>
; __device__ __forceinline__ void p0_transpose_matrix2(Frame& F, const float* W, int K, int N, bf16* WT, int nblk, CM colmap, RM rowmap, int& it0, const float* kgain = nullptr) {
;     ...
;     for (int r = first; r < nitems; r += F.ngw) {
;         const int kb = r / nblk, nb = r % nblk;
;         p0_transpose_item(W, K, N, WT, kb, colmap(nb), rowmap(nb), scr, F.lane, kgain);
;     }
;     it0 += nitems;
.Lcva_exit:
	s_waitcnt vmcnt(0)
	s_cmp_eq_u32 s32, 0
	s_cbranch_scc1 .Lcv_ret0
	s_cmp_eq_u32 s32, 1
	s_cbranch_scc1 .Lcv_ret1
	s_cmp_eq_u32 s32, 2
	s_cbranch_scc1 .Lcv_ret2
	s_cmp_eq_u32 s32, 3
	s_cbranch_scc1 .Lcv_ret3
	s_cmp_eq_u32 s32, 4
	s_cbranch_scc1 .Lcv_ret4
	s_branch .Lcv_ret7

; #define SEAM(k) do { if (lo <= (k) && (k) + 1 < hi) xcd_barrier(bar); } while (0)
; __device__ __forceinline__ void p0_rg_in(Frame& F, int my, int nconv) {
;     const int gw0 = F.gw, ngw0 = F.ngw; F.gw = my * NWAVES + F.wave; F.ngw = nconv * NWAVES;
;     int it0 = 0;
;     p0_transpose_matrix(F, FIN(F, 8), DM, RG_NP, (bf16*)FW(F, WS_W_RG_IN), RG_NP / 32, [](int nb) { return nb * 32; }, it0, FIN(F, 1) + 1 * DM);
;     F.gw = gw0; F.ngw = ngw0;
; }
; __global__ void __launch_bounds__(NTHREADS, 2) fwd_kernel(Args args) {
;     ...
;         if (F.G == 256 && blockIdx.x >= 160) { __syncthreads(); p0_rg_in(F, (int)blockIdx.x - 160, 96); } } SEAM(1);
.LBB0_450:
	v_readlane_b32 s2, v254, 13
	s_cmpk_lt_u32 s85, 0xa0
	v_readlane_b32 s3, v254, 14
	s_cselect_b64 s[0:1], -1, 0
	s_xor_b64 s[2:3], s[2:3], -1
	s_or_b64 s[0:1], s[0:1], s[2:3]
	s_and_b64 vcc, exec, s[0:1]
	s_cbranch_vccnz .LBB0_464
	v_readlane_b32 s4, v254, 7
	v_readlane_b32 s5, v254, 8
	s_waitcnt lgkmcnt(0)
	s_barrier
	v_readlane_b32 s62, v254, 7
	v_readlane_b32 s63, v254, 8
	s_nop 3
	s_load_dwordx2 s[44:45], s[62:63], 0x40
	s_load_dwordx2 s[52:53], s[62:63], 0x8
	s_waitcnt lgkmcnt(0)
	s_add_u32 s52, s52, 0x4000
	s_addc_u32 s53, s53, 0
	s_mov_b32 s46, 0x8000
	s_mov_b32 s47, 0
	s_add_u32 s48, s70, 0xf600000
	s_addc_u32 s49, s71, 0
	s_mov_b32 s50, 64
	s_mov_b32 s51, 0xc
	s_mov_b32 s54, 0
	s_mov_b32 s55, 0
	s_lshl_b32 s56, s85, 3
	s_add_i32 s56, s56, s90
	s_addk_i32 s56, 0xfb00
	s_mov_b32 s32, 7
	s_branch .Lcva_run
.Lcv_ret7:
.LBB0_464:
	v_readlane_b32 s0, v254, 0
	v_readlane_b32 s1, v254, 1
	v_readlane_b32 s2, v254, 2
	v_readlane_b32 s3, v254, 3
	s_cmp_gt_i32 s1, 2
	s_cselect_b64 s[2:3], -1, 0
	s_and_b64 s[0:1], s[6:7], s[2:3]
	s_andn2_b64 vcc, exec, s[0:1]
	s_cbranch_vccnz .LBB0_514
	s_waitcnt vmcnt(0)
	v_cmp_eq_u32_e32 vcc, 0, v0
	s_waitcnt lgkmcnt(0)
	s_barrier
	s_and_saveexec_b64 s[0:1], vcc
	s_cbranch_execz .LBB0_513
	v_mov_b32_e32 v1, s84
	s_waitcnt vmcnt(0) expcnt(0) lgkmcnt(0)
	ds_read_b32 v3, v1
	ds_read_b32 v1, v1 offset:4
	s_waitcnt lgkmcnt(1)
	v_cmp_ne_u32_e32 vcc, 0, v3
	s_cbranch_vccnz .LBB0_481
	v_readlane_b32 s4, v254, 4
	v_readlane_b32 s5, v254, 5
	s_load_dwordx2 s[8:9], s[4:5], 0x4
	s_add_u32 s4, s78, 0x1000
	s_addc_u32 s5, s79, 0
	s_add_u32 s6, s78, 0x1100
	s_addc_u32 s7, s79, 0
	s_waitcnt lgkmcnt(0)
	s_mul_i32 s18, s8, s83
	s_add_u32 s8, s78, 0x1200
	s_mul_i32 s18, s18, s9
	s_addc_u32 s9, s79, 0
	s_add_u32 s10, s78, 0x1300
	s_addc_u32 s11, s79, 0
	s_mov_b32 s19, 1
	v_mov_b32_e32 v17, 0
	s_branch .LBB0_469
